# phase-start LDS parameter staging (gngate 4 arrays, mix coefficients 6 rows): all loads in flight then one wait, instead of load-wait-write ladders (from v34)
# baseline (speedup 1.0000x reference)
; #define LAS __attribute__((address_space(3)))
; #define TID_OF(a) ((a).w0 * 64 + lane_opaque())
; #define INP(a, i) inp_(a, i)
; DI void gngate_phase(unsigned char* lds, const Ctx& a, const Op& d) {
;     ...
;         const int t_ = TID_OF(a);
;         const float *s0 = INP(a, 19) + ia * DM, *s1 = INP(a, 20) + ia * DM, *s2 = INP(a, 21) + ia * DM, *s3 = INP(a, 22) + ia * DM;
;         for (int i = t_ * 4; i < DM; i += NTHREADS * 4) { *(LAS f32x4*)(pl + i) = *(const f32x4*)(s0 + i); *(LAS f32x4*)(pl + DM + i) = *(const f32x4*)(s1 + i);
;             *(LAS f32x4*)(pl + 2 * DM + i) = *(const f32x4*)(s2 + i); *(LAS f32x4*)(pl + 3 * DM + i) = *(const f32x4*)(s3 + i); }
;         __syncthreads();
.LBB0_428:
	flat_load_dwordx4 v[10:13], v[6:7]
	flat_load_dwordx4 v[16:19], v[4:5]
	flat_load_dwordx4 v[20:23], v[2:3]
	flat_load_dwordx4 v[24:27], v[0:1]
	v_add_u32_e32 v8, 0x800, v8
	v_add_u32_e32 v14, 0x2000, v9
	v_cmp_lt_i32_e32 vcc, -1, v8
	v_lshl_add_u64 v[6:7], v[6:7], 0, s[14:15]
	s_or_b64 s[0:1], vcc, s[0:1]
	v_lshl_add_u64 v[4:5], v[4:5], 0, s[14:15]
	v_lshl_add_u64 v[2:3], v[2:3], 0, s[14:15]
	v_lshl_add_u64 v[0:1], v[0:1], 0, s[14:15]
	s_waitcnt vmcnt(0) lgkmcnt(0)
	ds_write_b128 v9, v[10:13]
	ds_write_b128 v9, v[16:19] offset:8192
	ds_write_b128 v9, v[20:23] offset:16384
	ds_write_b128 v9, v[24:27] offset:24576
	v_mov_b32_e32 v9, v14
	s_andn2_b64 exec, exec, s[0:1]
	s_cbranch_execnz .LBB0_428

; #define LAS __attribute__((address_space(3)))
; #define INP(a, i) inp_(a, i)
; DI void mix_phase(unsigned char* lds, const Ctx& a, const Op& d) {
;     ...
;         const float* gg = INP(a, 1) + d.layer * DM; const float* mg = INP(a, 4) + (size_t)d.idx * 6 * DM;
;         for (int i = tid * 4; i < DM; i += NTHREADS * 4) *(LAS f32x4*)(g + i) = *(const f32x4*)(gg + i);
;         for (int i = tid * 4; i < 6 * DM; i += NTHREADS * 4) *(LAS f32x4*)(mu + i) = *(const f32x4*)(mg + i);
;         __syncthreads();
;     }
.LBB0_549:
	flat_load_dwordx4 v[6:9], v[0:1]
	v_lshl_add_u64 v[0:1], v[0:1], 0, s[10:11]
	flat_load_dwordx4 v[10:13], v[0:1]
	v_lshl_add_u64 v[0:1], v[0:1], 0, s[10:11]
	flat_load_dwordx4 v[16:19], v[0:1]
	v_lshl_add_u64 v[0:1], v[0:1], 0, s[10:11]
	flat_load_dwordx4 v[20:23], v[0:1]
	v_lshl_add_u64 v[0:1], v[0:1], 0, s[10:11]
	flat_load_dwordx4 v[24:27], v[0:1]
	v_lshl_add_u64 v[0:1], v[0:1], 0, s[10:11]
	flat_load_dwordx4 v[28:31], v[0:1]
	s_movk_i32 s6, 0x27ff
	s_waitcnt vmcnt(0) lgkmcnt(0)
	ds_write_b128 v2, v[6:9]
	ds_write_b128 v2, v[10:13] offset:8192
	ds_write_b128 v2, v[16:19] offset:16384
	ds_write_b128 v2, v[20:23] offset:24576
	ds_write_b128 v2, v[24:27] offset:32768
	ds_write_b128 v2, v[28:31] offset:40960
